# counted-wait / loop-edge trims: one write wait per attention tile, key counter only in the peeled last pair, arrival spins poll without s_sleep
# baseline (speedup 1.0000x reference)
; __device__ __forceinline__ void fused_norm_tail(CA& A, int l, int s) {
;     ...
;     if (tid == 0) {
;         __hip_atomic_fetch_add(cnt, 1u, __ATOMIC_RELAXED, __HIP_MEMORY_SCOPE_AGENT);
;         unsigned spins = 0;
;         while (__hip_atomic_load(cnt, __ATOMIC_RELAXED, __HIP_MEMORY_SCOPE_AGENT) < 4u) { __builtin_amdgcn_s_sleep(2); if (++spins > (1u << 22)) break; }
;     }
.Lmy_tail_spin:
	global_load_dword v1, v0, s[46:47] sc1
	s_add_i32 s48, s48, 1
	s_waitcnt vmcnt(0)
	v_cmp_lt_u32_e32 vcc, 3, v1
	s_cbranch_vccnz .Lmy_tail_arrived
	s_cmp_lt_u32 s48, 0x400000
	s_cbranch_scc0 .Lmy_tail_arrived
	s_branch .Lmy_tail_spin

; #define LAS __attribute__((address_space(3)))
; template <bool DIFF>
; __device__ __forceinline__ void attn_unit(CA& A, int l, int b, int hh, int qb, LAS unsigned char* lds, float lam, float lam_init) {
;     ...
;         if (key0 <= qlast) {
;             const LAS unsigned char* Kb = lds + AL_KS + buf * AL_KSZ;
;             const LAS unsigned char* Vb = lds + AL_VT + buf * AL_VSZ;
;             f32x16 p[2];
; #pragma unroll
;             for (int kt = 0; kt < 2; ++kt) {
;                 if (!DIFF) {
;                     const LAS float* nc = (const LAS float*)(lds + AL_NC + buf * 512) + 32 * kt + 4 * hi;
; #pragma unroll
;                     for (int g = 0; g < 4; ++g) { const f32x4 c4 = *(const LAS f32x4*)(nc + 8 * g); p[kt][4 * g] = c4[0]; p[kt][4 * g + 1] = c4[1]; p[kt][4 * g + 2] = c4[2]; p[kt][4 * g + 3] = c4[3]; }
;                 }
; #pragma unroll
;                 for (int s = 0; s < NS; ++s) {
;                     const bf16x8 a = *(const LAS bf16x8*)(Kb + (32 * kt + r32) * 144 + (koff + 16 * s + 8 * hi) * 2);
;     ...
;             for (int kt = 0; kt < 2; ++kt)
; #pragma unroll
;                 for (int r = 0; r < 16; ++r) p[kt][r] = __builtin_amdgcn_exp2f(p[kt][r]);
;             bf16x8 pb[2][2];
; #pragma unroll
;             for (int kt = 0; kt < 2; ++kt)
; #pragma unroll
;                 for (int i = 0; i < 2; ++i) { v4u w;
; #pragma unroll
;                     for (int j = 0; j < 4; ++j) w[j] = pk2(p[kt][8 * i + 2 * j], p[kt][8 * i + 2 * j + 1]);
;                     pb[kt][i] = __builtin_bit_cast(bf16x8, w); }
; #pragma unroll
;             for (int kt = 0; kt < 2; ++kt)
; #pragma unroll
;                 for (int i = 0; i < 2; ++i) {
; #pragma unroll
;                     for (int dt = 0; dt < 2; ++dt) {
;                         const LAS unsigned char* vq = Vb + (32 * dt + r32) * 136 + (32 * kt + 16 * i + 4 * hi) * 2;
;                         const s16x4 lo = *(const LAS s16x4*)vq, h4 = *(const LAS s16x4*)(vq + 16);
;                         const bf16x8 a = {lo[0], lo[1], lo[2], lo[3], h4[0], h4[1], h4[2], h4[3]};
;                         o[dt] = __builtin_amdgcn_mfma_f32_32x32x16_bf16(a, pb[kt][i], o[dt], 0, 0, 0);
;                     }
;                     ol = __builtin_amdgcn_mfma_f32_32x32x16_bf16(ones, pb[kt][i], ol, 0, 0, 0);
;                 }
;         }
;         if (has_next) ATT_WRITE(buf ^ 1);
.Lmy_df0_pv:
	v_exp_f32_e32 v96, v96
	v_exp_f32_e32 v97, v97
	v_exp_f32_e32 v98, v98
	v_exp_f32_e32 v99, v99
	v_exp_f32_e32 v100, v100
	v_exp_f32_e32 v101, v101
	v_exp_f32_e32 v102, v102
	v_exp_f32_e32 v103, v103
	v_cvt_pk_bf16_f32 v6, v96, v97
	v_cvt_pk_bf16_f32 v7, v98, v99
	v_cvt_pk_bf16_f32 v8, v100, v101
	v_cvt_pk_bf16_f32 v9, v102, v103
	v_exp_f32_e32 v104, v104
	v_exp_f32_e32 v105, v105
	s_waitcnt lgkmcnt(6)
	v_mfma_f32_32x32x16_bf16 v[32:47], v[164:167], v[6:9], v[32:47]
	v_exp_f32_e32 v106, v106
	v_exp_f32_e32 v107, v107
	v_cvt_pk_bf16_f32 v208, v104, v105
	v_mfma_f32_32x32x16_bf16 v[16:31], v[168:171], v[6:9], v[16:31]
	v_exp_f32_e32 v108, v108
	v_exp_f32_e32 v109, v109
	v_cvt_pk_bf16_f32 v209, v106, v107
	v_mfma_f32_32x32x16_bf16 v[64:79], v[204:207], v[6:9], v[64:79]
	v_exp_f32_e32 v110, v110
	v_exp_f32_e32 v111, v111
	v_cvt_pk_bf16_f32 v210, v108, v109
	v_exp_f32_e32 v80, v80
	v_cvt_pk_bf16_f32 v211, v110, v111
	v_exp_f32_e32 v81, v81
	s_waitcnt lgkmcnt(4)
	v_mfma_f32_32x32x16_bf16 v[32:47], v[172:175], v[208:211], v[32:47]
	v_exp_f32_e32 v82, v82
	v_exp_f32_e32 v83, v83
	v_cvt_pk_bf16_f32 v6, v80, v81
	v_mfma_f32_32x32x16_bf16 v[16:31], v[180:183], v[208:211], v[16:31]
	v_exp_f32_e32 v84, v84
	v_exp_f32_e32 v85, v85
	v_cvt_pk_bf16_f32 v7, v82, v83
	v_mfma_f32_32x32x16_bf16 v[64:79], v[204:207], v[208:211], v[64:79]
	v_exp_f32_e32 v86, v86
	v_exp_f32_e32 v87, v87
	v_cvt_pk_bf16_f32 v8, v84, v85
	v_exp_f32_e32 v88, v88
	v_cvt_pk_bf16_f32 v9, v86, v87
	v_exp_f32_e32 v89, v89
	s_waitcnt lgkmcnt(2)
	v_mfma_f32_32x32x16_bf16 v[32:47], v[184:187], v[6:9], v[32:47]
	v_exp_f32_e32 v90, v90
	v_exp_f32_e32 v91, v91
	v_cvt_pk_bf16_f32 v208, v88, v89
	v_mfma_f32_32x32x16_bf16 v[16:31], v[188:191], v[6:9], v[16:31]
	v_exp_f32_e32 v92, v92
	v_exp_f32_e32 v93, v93
	v_cvt_pk_bf16_f32 v209, v90, v91
	v_mfma_f32_32x32x16_bf16 v[64:79], v[204:207], v[6:9], v[64:79]
	v_exp_f32_e32 v94, v94
	v_exp_f32_e32 v95, v95
	v_cvt_pk_bf16_f32 v210, v92, v93
	s_nop 0
	v_cvt_pk_bf16_f32 v211, v94, v95
	s_waitcnt lgkmcnt(0)
	s_nop 0
	v_mfma_f32_32x32x16_bf16 v[32:47], v[192:195], v[208:211], v[32:47]
	v_mfma_f32_32x32x16_bf16 v[16:31], v[196:199], v[208:211], v[16:31]
	v_mfma_f32_32x32x16_bf16 v[64:79], v[204:207], v[208:211], v[64:79]
	s_waitcnt vmcnt(0)
	ds_write_b128 v139, v[120:123] offset:9216
	ds_write_b16 v140, v124 offset:27136
	ds_write_b16_d16_hi v140, v124 offset:27272
	ds_write_b16 v140, v125 offset:27408
	ds_write_b16_d16_hi v140, v125 offset:27544
	ds_write_b16 v140, v126 offset:27680
	ds_write_b16_d16_hi v140, v126 offset:27816
	ds_write_b16 v140, v127 offset:27952
	ds_write_b16_d16_hi v140, v127 offset:28088
	s_add_i32 s26, s26, 64
	s_waitcnt lgkmcnt(0)
	s_barrier
	s_sub_i32 s30, s26, 63
	s_cmp_gt_u32 s30, s28
	s_cbranch_scc1 .Lmy_df_skip
	ds_read_b128 v[148:151], v200 offset:9216
	ds_read_b128 v[152:155], v201 offset:9216
	ds_read_b128 v[156:159], v200 offset:9248
	ds_read_b128 v[160:163], v201 offset:9248
	s_waitcnt lgkmcnt(2)
	v_mfma_f32_32x32x16_bf16 v[96:111], v[148:151], v[112:115], v[48:63]
	v_mfma_f32_32x32x16_bf16 v[80:95], v[152:155], v[112:115], v[48:63]
	s_waitcnt lgkmcnt(0)
	v_mfma_f32_32x32x16_bf16 v[96:111], v[156:159], v[116:119], v[96:111]
	v_mfma_f32_32x32x16_bf16 v[80:95], v[160:163], v[116:119], v[80:95]
	ds_read2_b64 v[164:167], v212 offset0:0 offset1:2
	ds_read2_b64 v[168:171], v213 offset0:32 offset1:34
	ds_read2_b64 v[172:175], v212 offset0:4 offset1:6
	ds_read2_b64 v[180:183], v213 offset0:36 offset1:38
	ds_read2_b64 v[184:187], v212 offset0:8 offset1:10
	ds_read2_b64 v[188:191], v213 offset0:40 offset1:42
	ds_read2_b64 v[192:195], v212 offset0:12 offset1:14
	ds_read2_b64 v[196:199], v213 offset0:44 offset1:46
	s_cmp_le_u32 s26, s25
	s_nop 1
	s_cbranch_scc1 .Lmy_df1_pv
; __device__ __forceinline__ int crow(int r, int hi) { return (r & 3) + 8 * (r >> 2) + 4 * hi; }
; template <bool DIFF>
; __device__ __forceinline__ void attn_unit(CA& A, int l, int b, int hh, int qb, LAS unsigned char* lds, float lam, float lam_init) {
;     ...
;             if (key0 + 63 > qfirst) {
; #pragma unroll
;                 for (int kt = 0; kt < 2; ++kt)
; #pragma unroll
;                     for (int r = 0; r < 16; ++r) if (key0 + 32 * kt + crow(r, hi) > qmine) p[kt][r] = -1e30f;
;             }
	v_add_u32_e32 v1, s26, v131
	v_subrev_u32_e32 v2, 63, v1
	v_cmp_gt_u32_e32 vcc, v2, v138
	s_nop 1
	v_cndmask_b32_e32 v3, v96, v225, vcc
	v_cmp_lt_u32_e32 vcc, v2, v138
	v_subrev_u32_e32 v2, 61, v1
	s_nop 0
	v_cndmask_b32_e32 v96, v3, v96, vcc
	v_cndmask_b32_e32 v97, v225, v97, vcc
	v_cmp_le_u32_e32 vcc, v2, v138
	v_subrev_u32_e32 v2, 60, v1
	s_nop 0
	v_cndmask_b32_e32 v98, v225, v98, vcc
	v_cmp_le_u32_e32 vcc, v2, v138
	v_subrev_u32_e32 v2, 55, v1
	s_nop 0
	v_cndmask_b32_e32 v99, v225, v99, vcc
	v_cmp_le_u32_e32 vcc, v2, v138
	v_subrev_u32_e32 v2, 54, v1
	s_nop 0
	v_cndmask_b32_e32 v100, v225, v100, vcc
	v_cmp_le_u32_e32 vcc, v2, v138
	v_subrev_u32_e32 v2, 53, v1
	s_nop 0
	v_cndmask_b32_e32 v101, v225, v101, vcc
	v_cmp_le_u32_e32 vcc, v2, v138
	v_subrev_u32_e32 v2, 52, v1
	s_nop 0
	v_cndmask_b32_e32 v102, v225, v102, vcc
	v_cmp_le_u32_e32 vcc, v2, v138
	v_subrev_u32_e32 v2, 47, v1
	s_nop 0
	v_cndmask_b32_e32 v103, v225, v103, vcc
	v_cmp_le_u32_e32 vcc, v2, v138
	v_subrev_u32_e32 v2, 46, v1
	s_nop 0
	v_cndmask_b32_e32 v104, v225, v104, vcc
	v_cmp_le_u32_e32 vcc, v2, v138
	v_subrev_u32_e32 v2, 45, v1
	s_nop 0
	v_cndmask_b32_e32 v105, v225, v105, vcc
	v_cmp_le_u32_e32 vcc, v2, v138
	v_subrev_u32_e32 v2, 44, v1
	s_nop 0
	v_cndmask_b32_e32 v106, v225, v106, vcc
	v_cmp_le_u32_e32 vcc, v2, v138
	v_subrev_u32_e32 v2, 39, v1
	s_nop 0
	v_cndmask_b32_e32 v107, v225, v107, vcc
	v_cmp_le_u32_e32 vcc, v2, v138
	v_subrev_u32_e32 v2, 38, v1
	s_nop 0
	v_cndmask_b32_e32 v108, v225, v108, vcc
	v_cmp_le_u32_e32 vcc, v2, v138
	v_subrev_u32_e32 v2, 37, v1
	s_nop 0
	v_cndmask_b32_e32 v109, v225, v109, vcc
	v_cmp_le_u32_e32 vcc, v2, v138
	v_subrev_u32_e32 v2, 36, v1
	s_nop 0
	v_cndmask_b32_e32 v110, v225, v110, vcc
	v_cmp_le_u32_e32 vcc, v2, v138
	v_subrev_u32_e32 v2, 31, v1
	s_nop 0
	v_cndmask_b32_e32 v111, v225, v111, vcc
	v_cmp_le_u32_e32 vcc, v2, v138
	v_subrev_u32_e32 v2, 30, v1
	s_nop 0
	v_cndmask_b32_e32 v80, v225, v80, vcc
	v_cmp_le_u32_e32 vcc, v2, v138
	v_subrev_u32_e32 v2, 29, v1
	s_nop 0
	v_cndmask_b32_e32 v81, v225, v81, vcc
	v_cmp_le_u32_e32 vcc, v2, v138
	v_subrev_u32_e32 v2, 28, v1
	s_nop 0
	v_cndmask_b32_e32 v82, v225, v82, vcc
	v_cmp_le_u32_e32 vcc, v2, v138
	v_subrev_u32_e32 v2, 23, v1
	s_nop 0
	v_cndmask_b32_e32 v83, v225, v83, vcc
	v_cmp_le_u32_e32 vcc, v2, v138
	v_subrev_u32_e32 v2, 22, v1
	s_nop 0
	v_cndmask_b32_e32 v84, v225, v84, vcc
	v_cmp_le_u32_e32 vcc, v2, v138
	v_subrev_u32_e32 v2, 21, v1
	s_nop 0
	v_cndmask_b32_e32 v85, v225, v85, vcc
	v_cmp_le_u32_e32 vcc, v2, v138
	v_subrev_u32_e32 v2, 20, v1
	s_nop 0
	v_cndmask_b32_e32 v86, v225, v86, vcc
	v_cmp_le_u32_e32 vcc, v2, v138
	v_add_u32_e32 v2, -15, v1
	s_nop 0
	v_cndmask_b32_e32 v87, v225, v87, vcc
	v_cmp_le_u32_e32 vcc, v2, v138
	v_add_u32_e32 v2, -14, v1
	s_nop 0
	v_cndmask_b32_e32 v88, v225, v88, vcc
	v_cmp_le_u32_e32 vcc, v2, v138
	v_add_u32_e32 v2, -13, v1
	s_nop 0
	v_cndmask_b32_e32 v89, v225, v89, vcc
	v_cmp_le_u32_e32 vcc, v2, v138
	v_add_u32_e32 v2, -12, v1
	s_nop 0
	v_cndmask_b32_e32 v90, v225, v90, vcc
	v_cmp_le_u32_e32 vcc, v2, v138
	v_add_u32_e32 v2, -7, v1
	s_nop 0
	v_cndmask_b32_e32 v91, v225, v91, vcc
	v_cmp_le_u32_e32 vcc, v2, v138
	v_add_u32_e32 v2, -6, v1
	s_nop 0
	v_cndmask_b32_e32 v92, v225, v92, vcc
	v_cmp_le_u32_e32 vcc, v2, v138
	v_add_u32_e32 v2, -5, v1
	v_add_u32_e32 v1, -4, v1
	v_cndmask_b32_e32 v93, v225, v93, vcc
	v_cmp_le_u32_e32 vcc, v2, v138
	s_nop 1
	v_cndmask_b32_e32 v94, v225, v94, vcc
	v_cmp_le_u32_e32 vcc, v1, v138
	s_nop 1
	v_cndmask_b32_e32 v95, v225, v95, vcc

.Lmy_panel_spin:
	global_load_dword v4, v1, s[6:7] sc1
	global_load_dword v5, v2, s[6:7] sc1
	global_load_dword v6, v3, s[6:7] sc1
	global_load_dword v7, v9, s[6:7] sc1
	s_add_i32 s13, s13, 1
	s_waitcnt vmcnt(0)
	v_min3_u32 v4, v4, v5, v6
	v_cmp_le_u32_e64 s[14:15], s12, v4
	v_cmp_le_u32_e64 s[16:17], s11, v7
	s_nop 1
	s_and_b64 vcc, s[14:15], s[16:17]
	s_cbranch_vccnz .Lmy_panel_done
	s_cmp_lt_u32 s13, 0x200000
	s_cbranch_scc0 .Lmy_panel_done
	s_branch .Lmy_panel_spin
